# MLA loop bodies shifted by 4 bytes relative to the 64-byte aligned heads (instruction fetch phase comparison)
# baseline (speedup 1.0000x reference)
; #define LAS __attribute__((address_space(3)))
; template <int DQK, int VO = KL<DQK>::VOFF> __device__ __forceinline__ void stage_store(const Stage<DQK>& s, LAS unsigned char* lds, bool withV, int tid) {
;     { const int key = tid >> 3, c = tid & 7; *(LAS v4u*)(lds + k_off<DQK>(key, c)) = s.k0; }
;     if (DQK == 96) { if (tid < 256) { const int key = tid >> 2, c = tid & 3; *(LAS v4u*)(lds + k_off<DQK>(key, 8 + c)) = s.k1; } }
;     if (withV) { const int key = tid >> 3, c = tid & 7; *(LAS v4u*)(lds + VO + (key * VSTR + 8 * c) * 2) = s.v; }
; }
.Lmla_it0:
	s_nop 0
	s_add_i32 s96, s49, 2
	s_cmp_gt_u32 s96, s8
	s_cbranch_scc1 .Lmla_nostage0
	s_waitcnt vmcnt(0)
	ds_write_b128 v155, v[60:63] offset:53248
	ds_write_b128 v159, v[68:71] offset:53248
	s_cmp_eq_u32 s63, 0
	s_cbranch_scc1 .Lmla_nok1_10
	ds_write_b128 v157, v[64:67] offset:53248

; #define LAS __attribute__((address_space(3)))
; template <int DQK, int VO = KL<DQK>::VOFF> __device__ __forceinline__ void stage_store(const Stage<DQK>& s, LAS unsigned char* lds, bool withV, int tid) {
;     { const int key = tid >> 3, c = tid & 7; *(LAS v4u*)(lds + k_off<DQK>(key, c)) = s.k0; }
;     if (DQK == 96) { if (tid < 256) { const int key = tid >> 2, c = tid & 3; *(LAS v4u*)(lds + k_off<DQK>(key, 8 + c)) = s.k1; } }
;     if (withV) { const int key = tid >> 3, c = tid & 7; *(LAS v4u*)(lds + VO + (key * VSTR + 8 * c) * 2) = s.v; }
; }
.Lmla_it1:
	s_nop 0
	s_add_i32 s96, s49, 2
	s_cmp_gt_u32 s96, s8
	s_cbranch_scc1 .Lmla_nostage1
	s_waitcnt vmcnt(0)
	ds_write_b128 v155, v[60:63]
	ds_write_b128 v159, v[68:71]
	s_cmp_eq_u32 s63, 0
	s_cbranch_scc1 .Lmla_nok1_11
	ds_write_b128 v157, v[64:67]

; #define LAS __attribute__((address_space(3)))
; template <int DQK, int VO = KL<DQK>::VOFF> __device__ __forceinline__ void stage_store(const Stage<DQK>& s, LAS unsigned char* lds, bool withV, int tid) {
;     { const int key = tid >> 3, c = tid & 7; *(LAS v4u*)(lds + k_off<DQK>(key, c)) = s.k0; }
;     if (DQK == 96) { if (tid < 256) { const int key = tid >> 2, c = tid & 3; *(LAS v4u*)(lds + k_off<DQK>(key, 8 + c)) = s.k1; } }
;     if (withV) { const int key = tid >> 3, c = tid & 7; *(LAS v4u*)(lds + VO + (key * VSTR + 8 * c) * 2) = s.v; }
; }
.Lmla_it2:
	s_nop 0
	s_add_i32 s96, s49, 2
	s_cmp_gt_u32 s96, s8
	s_cbranch_scc1 .Lmla_nostage2
	s_waitcnt vmcnt(0)
	ds_write_b128 v155, v[60:63] offset:26624
	ds_write_b128 v159, v[68:71] offset:26624
	s_cmp_eq_u32 s63, 0
	s_cbranch_scc1 .Lmla_nok1_12
	ds_write_b128 v157, v[64:67] offset:26624
